# sample retention units: gain/gate loads hoisted to the item start, no full vmcnt drain at sample and kv item boundaries
# baseline (speedup 1.0000x reference)
; #define LAS __attribute__((address_space(3)))
; __device__ __forceinline__ int launder(int v) { asm volatile("" : "+v"(v)); return v; }
; __device__ __forceinline__ float lg2gamma(int h) { return log1pf(-exp2f(-5.0f - (float)h)) * 1.4426950408889634f; }
; __device__ __forceinline__ void chunk_geom(int unit, int& b, int& h, int& c, int& n, int& R0, int& slot) {
;     int bh; if (unit < 32) { bh = unit; c = 0; } else { bh = (unit - 32) >> 4; c = 1 + ((unit - 32) & 15); }
;     b = bh >> 3; h = bh & 7;
;     n = c ? 128 : 16; R0 = MS + b * LP + (c ? 16 + 128 * (c - 1) : 0); slot = bh * 17 + c;
; }
; __device__ void kv_unit(const Params& p, int unit, LAS unsigned char* lds, const int tid_in) {
;     const int tid = launder(tid_in); const int wid = __builtin_amdgcn_readfirstlane(tid >> 6);
;     int b, h, c, n, R0, slot; chunk_geom(unit, b, h, c, n, R0, slot);
;     const float lg = lg2gamma(h);
;     const bf16_t* zb = (const bf16_t*)(pws(p) + OFF_ZB) + (size_t)R0 * ZW + h * 256;
;     LAS unsigned char* regA = lds; LAS unsigned char* regB = lds + 65536;
;     load_tile<true>(regA, zb + ZC_K, ZW, n, lg, tid);
;     load_tile<false>(regB, zb + ZC_V, ZW, n, 0.f, tid);
.LBB0_484:
	s_mov_b64 s[0:1], 0
	s_and_b64 vcc, exec, s[6:7]
	s_mov_b64 s[6:7], 0
	s_cbranch_vccz .LBB0_522
	s_and_b32 s7, s38, 15
	s_add_i32 s6, s38, 0xfffffc00
	s_add_i32 s7, s7, 1
	s_cmp_lt_u32 s6, 32
	s_cselect_b32 s40, 0, s7
	s_lshl_b32 s7, s40, 7
	s_addk_i32 s7, 0xff90
	s_cmp_lt_u32 s6, 32
	s_cselect_b32 s33, 16, 0x80
	s_cselect_b32 s7, 0, s7
	s_add_i32 s8, s38, 0xfffffbe0
	s_lshr_b32 s8, s8, 4
	s_cmp_lt_u32 s6, 32
	s_cselect_b32 s41, s6, s8
	s_and_b32 s8, s41, 7
	v_cvt_f32_ubyte0_e32 v0, s8
	v_sub_f32_e32 v0, 0xc0a00000, v0
	v_cmp_gt_f32_e32 vcc, s75, v0
	s_lshr_b32 s6, s41, 3
	s_mulk_i32 s6, 0x810
	v_cndmask_b32_e32 v2, 0, v237, vcc
	v_add_f32_e32 v0, v0, v2
	s_add_i32 s6, s6, s7
	v_exp_f32_e32 v0, v0
	s_add_i32 s9, s6, 0x400
	s_and_b64 s[6:7], vcc, exec
	s_cselect_b32 s6, 0xffffffc0, 0
	v_ldexp_f32 v0, v0, s6
	v_sub_f32_e32 v4, 1.0, v0
	v_add_f32_e32 v2, -1.0, v4
	v_sub_f32_e32 v3, v2, v4
	v_add_f32_e32 v3, 1.0, v3
	v_sub_f32_e64 v2, -v0, v2
	v_add_f32_e32 v5, v2, v3
	v_frexp_mant_f32_e32 v6, v4
	v_cvt_f64_f32_e32 v[2:3], v4
	s_mov_b32 s6, 0x3f2aaaab
	v_frexp_exp_i32_f64_e32 v2, v[2:3]
	v_cmp_gt_f32_e32 vcc, s6, v6
	s_mov_b32 s6, 0x3f317218
	v_readlane_b32 s10, v253, 19
	v_subbrev_co_u32_e32 v2, vcc, 0, v2, vcc
	v_sub_u32_e32 v3, 0, v2
	v_ldexp_f32 v4, v4, v3
	v_ldexp_f32 v3, v5, v3
	v_add_f32_e32 v5, -1.0, v4
	v_add_f32_e32 v8, 1.0, v4
	v_add_f32_e32 v6, 1.0, v5
	v_add_f32_e32 v9, -1.0, v8
	v_sub_f32_e32 v6, v4, v6
	v_sub_f32_e32 v4, v4, v9
	v_add_f32_e32 v6, v3, v6
	v_add_f32_e32 v3, v3, v4
	v_add_f32_e32 v4, v8, v3
	v_rcp_f32_e32 v9, v4
	v_add_f32_e32 v7, v5, v6
	v_sub_f32_e32 v5, v7, v5
	v_sub_f32_e32 v5, v6, v5
	v_sub_f32_e32 v6, v4, v8
	v_sub_f32_e32 v3, v3, v6
	v_mul_f32_e32 v6, v7, v9
	v_mul_f32_e32 v8, v4, v6
	v_fma_f32 v10, v6, v4, -v8
	v_fmac_f32_e32 v10, v6, v3
	v_add_f32_e32 v11, v8, v10
	v_sub_f32_e32 v12, v7, v11
	v_sub_f32_e32 v7, v7, v12
	v_sub_f32_e32 v8, v11, v8
	v_sub_f32_e32 v7, v7, v11
	v_add_f32_e32 v5, v5, v7
	v_sub_f32_e32 v7, v8, v10
	v_add_f32_e32 v5, v7, v5
	v_add_f32_e32 v7, v12, v5
	v_mul_f32_e32 v8, v9, v7
	v_mul_f32_e32 v10, v4, v8
	v_fma_f32 v4, v8, v4, -v10
	v_fmac_f32_e32 v4, v8, v3
	v_sub_f32_e32 v3, v12, v7
	v_add_f32_e32 v3, v5, v3
	v_add_f32_e32 v5, v10, v4
	v_sub_f32_e32 v11, v7, v5
	v_sub_f32_e32 v7, v7, v11
	v_sub_f32_e32 v10, v5, v10
	v_sub_f32_e32 v5, v7, v5
	v_add_f32_e32 v3, v3, v5
	v_sub_f32_e32 v4, v10, v4
	v_cvt_f32_i32_e32 v2, v2
	v_add_f32_e32 v3, v4, v3
	v_add_f32_e32 v4, v6, v8
	v_add_f32_e32 v3, v11, v3
	v_sub_f32_e32 v5, v4, v6
	v_mul_f32_e32 v3, v9, v3
	v_sub_f32_e32 v5, v8, v5
	v_add_f32_e32 v3, v5, v3
	v_mul_f32_e32 v8, 0x3f317218, v2
	v_add_f32_e32 v5, v4, v3
	v_fma_f32 v9, v2, s6, -v8
	v_mul_f32_e32 v6, v5, v5
	v_fmac_f32_e32 v9, 0xb102e308, v2
	v_sub_f32_e32 v2, v5, v4
	v_fmamk_f32 v7, v6, 0x3e9b6dac, v234
	v_sub_f32_e32 v2, v3, v2
	v_add_f32_e32 v3, v8, v9
	v_fmaak_f32 v7, v6, v7, 0x3f2aaada
	v_sub_f32_e32 v4, v3, v8
	v_ldexp_f32 v8, v5, 1
	v_mul_f32_e32 v5, v5, v6
	v_mul_f32_e32 v5, v5, v7
	v_add_f32_e32 v6, v8, v5
	v_sub_f32_e32 v7, v6, v8
	v_ldexp_f32 v2, v2, 1
	v_sub_f32_e32 v5, v5, v7
	v_add_f32_e32 v2, v2, v5
	v_add_f32_e32 v5, v6, v2
	v_sub_f32_e32 v6, v5, v6
	v_sub_f32_e32 v2, v2, v6
	v_add_f32_e32 v6, v3, v5
	v_sub_f32_e32 v7, v6, v3
	v_sub_f32_e32 v8, v6, v7
	v_sub_f32_e32 v4, v9, v4
	v_sub_f32_e32 v3, v3, v8
	v_sub_f32_e32 v5, v5, v7
	v_add_f32_e32 v3, v5, v3
	v_add_f32_e32 v5, v4, v2
	v_sub_f32_e32 v7, v5, v4
	v_sub_f32_e32 v8, v5, v7
	v_sub_f32_e32 v4, v4, v8
	v_sub_f32_e32 v2, v2, v7
	v_add_f32_e32 v3, v5, v3
	v_add_f32_e32 v2, v2, v4
	v_add_f32_e32 v4, v6, v3
	v_sub_f32_e32 v5, v4, v6
	v_sub_f32_e32 v3, v3, v5
	v_add_f32_e32 v2, v2, v3
	v_add_f32_e32 v2, v4, v2
	v_cmp_nlt_f32_e32 vcc, 1.0, v0
	s_mov_b32 s6, 0x33800000
	v_mov_b32_e32 v34, v244
	v_cndmask_b32_e32 v2, v238, v2, vcc
	v_cmp_neq_f32_e32 vcc, 1.0, v0
	v_readlane_b32 s11, v253, 20
	v_mov_b32_e32 v6, 0
	v_cndmask_b32_e32 v2, v239, v2, vcc
	v_cmp_gt_f32_e32 vcc, s6, v0
	s_mul_hi_u32 s6, s9, 0x7000
	s_mulk_i32 s9, 0x7000
	s_add_u32 s7, s10, s9
	v_cndmask_b32_e64 v0, v2, -v0, vcc
	s_addc_u32 s6, s11, s6
	s_lshl_b32 s8, s8, 9
	v_lshlrev_b32_e32 v3, 3, v34
	v_mul_f32_e32 v12, 0x3fb8aa3b, v0
	s_add_u32 s28, s7, s8
	v_and_b32_e32 v0, 0xf8, v3
	s_addc_u32 s29, s6, 0
	v_lshlrev_b32_e32 v0, 1, v0
	v_lshl_add_u64 v[4:5], s[28:29], 0, v[0:1]
	s_mov_b64 s[6:7], 0x2000
	v_ashrrev_i32_e32 v10, 5, v34
	v_readfirstlane_b32 s39, v34
	v_mul_u32_u24_e32 v3, 0x7000, v10
	v_and_b32_e32 v4, 3, v10
	v_bfe_u32 v5, v10, 2, 2
	v_lshl_or_b32 v4, v4, 2, v5
	v_and_b32_e32 v5, 15, v34
	v_xor_b32_e32 v4, v4, v5
	v_lshlrev_b32_e32 v4, 4, v4
	v_lshl_add_u32 v4, v10, 8, v4
	v_bfe_u32 v5, v34, 4, 1
	v_lshl_add_u32 v2, v5, 15, v4
	v_add_u32_e32 v3, v3, v0
	v_add_u32_e32 v5, 0x10000, v2
	s_add_u32 s6, s28, 0x2000
	s_addc_u32 s7, s29, 0
	s_add_u32 s8, s28, 0x3000
	s_addc_u32 s9, s29, 0
	s_add_i32 s10, s33, -1
	v_sub_u32_e32 v6, s10, v10
	s_cmp_eq_u32 s33, 16
	s_cbranch_scc1 .Lkv_small
; #define LAS __attribute__((address_space(3)))
; __device__ __forceinline__ unsigned pk_bf16(float lo, float hi) { unsigned r; asm volatile("v_cvt_pk_bf16_f32 %0, %1, %2" : "=v"(r) : "v"(lo), "v"(hi)); return r; }
; __device__ __forceinline__ float bf_lo(unsigned u) { return __uint_as_float(u << 16); }
; __device__ __forceinline__ float bf_hi(unsigned u) { return __uint_as_float(u & 0xffff0000u); }
; template <bool SCALE>
; __device__ __forceinline__ void load_tile(LAS unsigned char* dst, const bf16_t* src, size_t ld, int nvalid, float lg, int tid) {
; #pragma unroll
;     for (int i = 0; i < 8; ++i) {
;         const int idx = i * 512 + tid, row = idx >> 5, ch = idx & 31;
;         u32x4 v = (u32x4){0u, 0u, 0u, 0u};
;         if (row < nvalid) {
;             v = *(const u32x4*)(src + (size_t)row * ld + ch * 8);
;             if (SCALE) { const float f = exp2f(lg * (float)(nvalid - 1 - row));
;                 v.x = pk_bf16(bf_lo(v.x) * f, bf_hi(v.x) * f); v.y = pk_bf16(bf_lo(v.y) * f, bf_hi(v.y) * f);
;                 v.z = pk_bf16(bf_lo(v.z) * f, bf_hi(v.z) * f); v.w = pk_bf16(bf_lo(v.w) * f, bf_hi(v.w) * f); }
;         }
;         *(LAS u32x4*)(dst + img_off(row, ch * 8)) = v;
;     }
; }
	global_load_dwordx4 v[64:67], v3, s[6:7]
	s_add_u32 s6, s6, 0x70000
	s_addc_u32 s7, s7, 0
	global_load_dwordx4 v[68:71], v3, s[6:7]
	s_add_u32 s6, s6, 0x70000
	s_addc_u32 s7, s7, 0
	global_load_dwordx4 v[72:75], v3, s[6:7]
	s_add_u32 s6, s6, 0x70000
	s_addc_u32 s7, s7, 0
	global_load_dwordx4 v[76:79], v3, s[6:7]
	s_add_u32 s6, s6, 0x70000
	s_addc_u32 s7, s7, 0
	global_load_dwordx4 v[80:83], v3, s[6:7]
	s_add_u32 s6, s6, 0x70000
	s_addc_u32 s7, s7, 0
	global_load_dwordx4 v[84:87], v3, s[6:7]
	s_add_u32 s6, s6, 0x70000
	s_addc_u32 s7, s7, 0
	global_load_dwordx4 v[88:91], v3, s[6:7]
	s_add_u32 s6, s6, 0x70000
	s_addc_u32 s7, s7, 0
	global_load_dwordx4 v[92:95], v3, s[6:7]
	global_load_dwordx4 v[96:99], v3, s[8:9]
	s_add_u32 s8, s8, 0x70000
	s_addc_u32 s9, s9, 0
	global_load_dwordx4 v[100:103], v3, s[8:9]
	s_add_u32 s8, s8, 0x70000
	s_addc_u32 s9, s9, 0
	global_load_dwordx4 v[104:107], v3, s[8:9]
	s_add_u32 s8, s8, 0x70000
	s_addc_u32 s9, s9, 0
	global_load_dwordx4 v[108:111], v3, s[8:9]
	s_add_u32 s8, s8, 0x70000
	s_addc_u32 s9, s9, 0
	global_load_dwordx4 v[112:115], v3, s[8:9]
	s_add_u32 s8, s8, 0x70000
	s_addc_u32 s9, s9, 0
	global_load_dwordx4 v[116:119], v3, s[8:9]
	s_add_u32 s8, s8, 0x70000
	s_addc_u32 s9, s9, 0
	global_load_dwordx4 v[120:123], v3, s[8:9]
	s_add_u32 s8, s8, 0x70000
	s_addc_u32 s9, s9, 0
	global_load_dwordx4 v[124:127], v3, s[8:9]
	v_mov_b32_e32 v7, v6
	v_cvt_f32_i32_e32 v7, v7
	v_mul_f32_e32 v7, v12, v7
	v_exp_f32_e32 v16, v7
	v_subrev_u32_e32 v7, 16, v6
	v_cvt_f32_i32_e32 v7, v7
	v_mul_f32_e32 v7, v12, v7
	v_exp_f32_e32 v17, v7
	v_subrev_u32_e32 v7, 32, v6
	v_cvt_f32_i32_e32 v7, v7
	v_mul_f32_e32 v7, v12, v7
	v_exp_f32_e32 v18, v7
	v_subrev_u32_e32 v7, 48, v6
	v_cvt_f32_i32_e32 v7, v7
	v_mul_f32_e32 v7, v12, v7
	v_exp_f32_e32 v19, v7
	v_subrev_u32_e32 v7, 64, v6
	v_cvt_f32_i32_e32 v7, v7
	v_mul_f32_e32 v7, v12, v7
	v_exp_f32_e32 v20, v7
	v_subrev_u32_e32 v7, 80, v6
	v_cvt_f32_i32_e32 v7, v7
	v_mul_f32_e32 v7, v12, v7
	v_exp_f32_e32 v21, v7
	v_subrev_u32_e32 v7, 96, v6
	v_cvt_f32_i32_e32 v7, v7
	v_mul_f32_e32 v7, v12, v7
	v_exp_f32_e32 v22, v7
	v_subrev_u32_e32 v7, 112, v6
	v_cvt_f32_i32_e32 v7, v7
	v_mul_f32_e32 v7, v12, v7
	v_exp_f32_e32 v23, v7
	s_nop 0
	s_waitcnt vmcnt(15)
	v_lshlrev_b32_e32 v24, 16, v64
	v_and_b32_e32 v64, 0xffff0000, v64
	v_lshlrev_b32_e32 v25, 16, v65
	v_and_b32_e32 v65, 0xffff0000, v65
	v_lshlrev_b32_e32 v26, 16, v66
	v_and_b32_e32 v66, 0xffff0000, v66
	v_lshlrev_b32_e32 v27, 16, v67
	v_and_b32_e32 v67, 0xffff0000, v67
	v_mul_f32_e32 v24, v16, v24
	v_mul_f32_e32 v64, v16, v64
	v_mul_f32_e32 v25, v16, v25
	v_mul_f32_e32 v65, v16, v65
	v_mul_f32_e32 v26, v16, v26
	v_mul_f32_e32 v66, v16, v66
	v_mul_f32_e32 v27, v16, v27
	v_mul_f32_e32 v67, v16, v67
	v_cvt_pk_bf16_f32 v64, v24, v64
	v_cvt_pk_bf16_f32 v65, v25, v65
	v_cvt_pk_bf16_f32 v66, v26, v66
	v_cvt_pk_bf16_f32 v67, v27, v67
	ds_write_b128 v2, v[64:67] offset:0
	s_waitcnt vmcnt(14)
	v_lshlrev_b32_e32 v24, 16, v68
	v_and_b32_e32 v68, 0xffff0000, v68
	v_lshlrev_b32_e32 v25, 16, v69
	v_and_b32_e32 v69, 0xffff0000, v69
	v_lshlrev_b32_e32 v26, 16, v70
	v_and_b32_e32 v70, 0xffff0000, v70
	v_lshlrev_b32_e32 v27, 16, v71
	v_and_b32_e32 v71, 0xffff0000, v71
	v_mul_f32_e32 v24, v17, v24
	v_mul_f32_e32 v68, v17, v68
	v_mul_f32_e32 v25, v17, v25
	v_mul_f32_e32 v69, v17, v69
	v_mul_f32_e32 v26, v17, v26
	v_mul_f32_e32 v70, v17, v70
	v_mul_f32_e32 v27, v17, v27
	v_mul_f32_e32 v71, v17, v71
	v_cvt_pk_bf16_f32 v68, v24, v68
	v_cvt_pk_bf16_f32 v69, v25, v69
	v_cvt_pk_bf16_f32 v70, v26, v70
	v_cvt_pk_bf16_f32 v71, v27, v71
	ds_write_b128 v2, v[68:71] offset:4096
	s_waitcnt vmcnt(13)
	v_lshlrev_b32_e32 v24, 16, v72
	v_and_b32_e32 v72, 0xffff0000, v72
	v_lshlrev_b32_e32 v25, 16, v73
	v_and_b32_e32 v73, 0xffff0000, v73
	v_lshlrev_b32_e32 v26, 16, v74
	v_and_b32_e32 v74, 0xffff0000, v74
	v_lshlrev_b32_e32 v27, 16, v75
	v_and_b32_e32 v75, 0xffff0000, v75
	v_mul_f32_e32 v24, v18, v24
	v_mul_f32_e32 v72, v18, v72
	v_mul_f32_e32 v25, v18, v25
	v_mul_f32_e32 v73, v18, v73
	v_mul_f32_e32 v26, v18, v26
	v_mul_f32_e32 v74, v18, v74
	v_mul_f32_e32 v27, v18, v27
	v_mul_f32_e32 v75, v18, v75
	v_cvt_pk_bf16_f32 v72, v24, v72
	v_cvt_pk_bf16_f32 v73, v25, v73
	v_cvt_pk_bf16_f32 v74, v26, v74
	v_cvt_pk_bf16_f32 v75, v27, v75
	ds_write_b128 v2, v[72:75] offset:8192
	s_waitcnt vmcnt(12)
; #define LAS __attribute__((address_space(3)))
; __device__ __forceinline__ unsigned pk_bf16(float lo, float hi) { unsigned r; asm volatile("v_cvt_pk_bf16_f32 %0, %1, %2" : "=v"(r) : "v"(lo), "v"(hi)); return r; }
; __device__ __forceinline__ float bf_lo(unsigned u) { return __uint_as_float(u << 16); }
; __device__ __forceinline__ float bf_hi(unsigned u) { return __uint_as_float(u & 0xffff0000u); }
; template <bool SCALE>
; __device__ __forceinline__ void load_tile(LAS unsigned char* dst, const bf16_t* src, size_t ld, int nvalid, float lg, int tid) {
; #pragma unroll
;     for (int i = 0; i < 8; ++i) {
;         const int idx = i * 512 + tid, row = idx >> 5, ch = idx & 31;
;         u32x4 v = (u32x4){0u, 0u, 0u, 0u};
;         if (row < nvalid) {
;             v = *(const u32x4*)(src + (size_t)row * ld + ch * 8);
;             if (SCALE) { const float f = exp2f(lg * (float)(nvalid - 1 - row));
;                 v.x = pk_bf16(bf_lo(v.x) * f, bf_hi(v.x) * f); v.y = pk_bf16(bf_lo(v.y) * f, bf_hi(v.y) * f);
;                 v.z = pk_bf16(bf_lo(v.z) * f, bf_hi(v.z) * f); v.w = pk_bf16(bf_lo(v.w) * f, bf_hi(v.w) * f); }
;         }
;         *(LAS u32x4*)(dst + img_off(row, ch * 8)) = v;
;     }
; }
	v_lshlrev_b32_e32 v24, 16, v76
	v_and_b32_e32 v76, 0xffff0000, v76
	v_lshlrev_b32_e32 v25, 16, v77
	v_and_b32_e32 v77, 0xffff0000, v77
	v_lshlrev_b32_e32 v26, 16, v78
	v_and_b32_e32 v78, 0xffff0000, v78
	v_lshlrev_b32_e32 v27, 16, v79
	v_and_b32_e32 v79, 0xffff0000, v79
	v_mul_f32_e32 v24, v19, v24
	v_mul_f32_e32 v76, v19, v76
	v_mul_f32_e32 v25, v19, v25
	v_mul_f32_e32 v77, v19, v77
	v_mul_f32_e32 v26, v19, v26
	v_mul_f32_e32 v78, v19, v78
	v_mul_f32_e32 v27, v19, v27
	v_mul_f32_e32 v79, v19, v79
	v_cvt_pk_bf16_f32 v76, v24, v76
	v_cvt_pk_bf16_f32 v77, v25, v77
	v_cvt_pk_bf16_f32 v78, v26, v78
	v_cvt_pk_bf16_f32 v79, v27, v79
	ds_write_b128 v2, v[76:79] offset:12288
	s_waitcnt vmcnt(11)
	v_lshlrev_b32_e32 v24, 16, v80
	v_and_b32_e32 v80, 0xffff0000, v80
	v_lshlrev_b32_e32 v25, 16, v81
	v_and_b32_e32 v81, 0xffff0000, v81
	v_lshlrev_b32_e32 v26, 16, v82
	v_and_b32_e32 v82, 0xffff0000, v82
	v_lshlrev_b32_e32 v27, 16, v83
	v_and_b32_e32 v83, 0xffff0000, v83
	v_mul_f32_e32 v24, v20, v24
	v_mul_f32_e32 v80, v20, v80
	v_mul_f32_e32 v25, v20, v25
	v_mul_f32_e32 v81, v20, v81
	v_mul_f32_e32 v26, v20, v26
	v_mul_f32_e32 v82, v20, v82
	v_mul_f32_e32 v27, v20, v27
	v_mul_f32_e32 v83, v20, v83
	v_cvt_pk_bf16_f32 v80, v24, v80
	v_cvt_pk_bf16_f32 v81, v25, v81
	v_cvt_pk_bf16_f32 v82, v26, v82
	v_cvt_pk_bf16_f32 v83, v27, v83
	ds_write_b128 v2, v[80:83] offset:16384
	s_waitcnt vmcnt(10)
	v_lshlrev_b32_e32 v24, 16, v84
	v_and_b32_e32 v84, 0xffff0000, v84
	v_lshlrev_b32_e32 v25, 16, v85
	v_and_b32_e32 v85, 0xffff0000, v85
	v_lshlrev_b32_e32 v26, 16, v86
	v_and_b32_e32 v86, 0xffff0000, v86
	v_lshlrev_b32_e32 v27, 16, v87
	v_and_b32_e32 v87, 0xffff0000, v87
	v_mul_f32_e32 v24, v21, v24
	v_mul_f32_e32 v84, v21, v84
	v_mul_f32_e32 v25, v21, v25
	v_mul_f32_e32 v85, v21, v85
	v_mul_f32_e32 v26, v21, v26
	v_mul_f32_e32 v86, v21, v86
	v_mul_f32_e32 v27, v21, v27
	v_mul_f32_e32 v87, v21, v87
	v_cvt_pk_bf16_f32 v84, v24, v84
	v_cvt_pk_bf16_f32 v85, v25, v85
	v_cvt_pk_bf16_f32 v86, v26, v86
	v_cvt_pk_bf16_f32 v87, v27, v87
	ds_write_b128 v2, v[84:87] offset:20480
	s_waitcnt vmcnt(9)
	v_lshlrev_b32_e32 v24, 16, v88
	v_and_b32_e32 v88, 0xffff0000, v88
	v_lshlrev_b32_e32 v25, 16, v89
	v_and_b32_e32 v89, 0xffff0000, v89
	v_lshlrev_b32_e32 v26, 16, v90
	v_and_b32_e32 v90, 0xffff0000, v90
	v_lshlrev_b32_e32 v27, 16, v91
	v_and_b32_e32 v91, 0xffff0000, v91
	v_mul_f32_e32 v24, v22, v24
	v_mul_f32_e32 v88, v22, v88
	v_mul_f32_e32 v25, v22, v25
	v_mul_f32_e32 v89, v22, v89
	v_mul_f32_e32 v26, v22, v26
	v_mul_f32_e32 v90, v22, v90
	v_mul_f32_e32 v27, v22, v27
	v_mul_f32_e32 v91, v22, v91
	v_cvt_pk_bf16_f32 v88, v24, v88
	v_cvt_pk_bf16_f32 v89, v25, v89
	v_cvt_pk_bf16_f32 v90, v26, v90
	v_cvt_pk_bf16_f32 v91, v27, v91
	ds_write_b128 v2, v[88:91] offset:24576
	s_waitcnt vmcnt(8)
	v_lshlrev_b32_e32 v24, 16, v92
	v_and_b32_e32 v92, 0xffff0000, v92
	v_lshlrev_b32_e32 v25, 16, v93
	v_and_b32_e32 v93, 0xffff0000, v93
	v_lshlrev_b32_e32 v26, 16, v94
	v_and_b32_e32 v94, 0xffff0000, v94
	v_lshlrev_b32_e32 v27, 16, v95
	v_and_b32_e32 v95, 0xffff0000, v95
	v_mul_f32_e32 v24, v23, v24
	v_mul_f32_e32 v92, v23, v92
	v_mul_f32_e32 v25, v23, v25
	v_mul_f32_e32 v93, v23, v93
	v_mul_f32_e32 v26, v23, v26
	v_mul_f32_e32 v94, v23, v94
	v_mul_f32_e32 v27, v23, v27
	v_mul_f32_e32 v95, v23, v95
	v_cvt_pk_bf16_f32 v92, v24, v92
	v_cvt_pk_bf16_f32 v93, v25, v93
	v_cvt_pk_bf16_f32 v94, v26, v94
	v_cvt_pk_bf16_f32 v95, v27, v95
	ds_write_b128 v2, v[92:95] offset:28672
	s_waitcnt vmcnt(7)
	ds_write_b128 v5, v[96:99] offset:0
	s_waitcnt vmcnt(6)
	ds_write_b128 v5, v[100:103] offset:4096
	s_waitcnt vmcnt(5)
	ds_write_b128 v5, v[104:107] offset:8192
	s_waitcnt vmcnt(4)
	ds_write_b128 v5, v[108:111] offset:12288
	s_waitcnt vmcnt(3)
	ds_write_b128 v5, v[112:115] offset:16384
	s_waitcnt vmcnt(2)
	ds_write_b128 v5, v[116:119] offset:20480
	s_waitcnt vmcnt(1)
	ds_write_b128 v5, v[120:123] offset:24576
	s_waitcnt vmcnt(0)
	ds_write_b128 v5, v[124:127] offset:28672
	s_branch .Lkv_join

; __device__ void sample_ret_unit(const Params& p, int l, int unit, LAS unsigned char* lds, const int tid_in) {
;     const int tid = launder(tid_in);
;     const int wid = tid >> 6, lane = tid & 63;
;     const int b = unit >> 3, h = unit & 7, r0 = b * 8;
;     const float lg = lg2gamma(h);
;     LAS float* sq = (LAS float*)lds; LAS float* sk = sq + 2048; LAS float* sv = sk + 2048; LAS float* sqT = sv + 2048; LAS float* skdT = sqT + 2048; LAS float* sc = skdT + 2048; LAS float* red = (LAS float*)(lds + 49152);
;     const bf16_t* zb = (const bf16_t*)(pws(p) + OFF_ZB);
;     { const int i = tid >> 6, d = (tid & 63) * 4; const bf16_t* zr = zb + (size_t)(r0 + i) * ZW + h * 256 + d;
;         const u32x2 a = *(const u32x2*)(zr + ZC_Q), kk = *(const u32x2*)(zr + ZC_K), vv = *(const u32x2*)(zr + ZC_V);
;         const float qf[4] = {bf_lo(a.x), bf_hi(a.x), bf_lo(a.y), bf_hi(a.y)}, kf[4] = {bf_lo(kk.x), bf_hi(kk.x), bf_lo(kk.y), bf_hi(kk.y)};
;         const float dk = exp2f(lg * (float)(7 - i));
;         *(LAS f32x4*)(sq + i * 256 + d) = (f32x4){qf[0], qf[1], qf[2], qf[3]};
;         *(LAS f32x4*)(sk + i * 256 + d) = (f32x4){kf[0], kf[1], kf[2], kf[3]};
;         *(LAS f32x4*)(sv + i * 256 + d) = (f32x4){bf_lo(vv.x), bf_hi(vv.x), bf_lo(vv.y), bf_hi(vv.y)};
; #pragma unroll
;         for (int j = 0; j < 4; ++j) { sqT[(d + j) * 8 + i] = qf[j]; skdT[(d + j) * 8 + i] = kf[j] * dk; } }
;     __syncthreads();
;     { const int i = wid; const f32x4 qv = *(const LAS f32x4*)(sq + i * 256 + lane * 4);
;         for (int j = 0; j < 8; ++j) { const f32x4 kv = *(const LAS f32x4*)(sk + j * 256 + lane * 4);
;             float s = wave_sum(qv[0] * kv[0] + qv[1] * kv[1] + qv[2] * kv[2] + qv[3] * kv[3]);
;             if (lane == 0) sc[i * 8 + j] = j <= i ? s * exp2f(lg * (float)(i - j)) : 0.f; } }
;     const int e4 = lane * 4;
;     f32x4 vv[8], oacc[8];
; #pragma unroll
;     for (int j = 0; j < 8; ++j) { vv[j] = *(const LAS f32x4*)(sv + j * 256 + e4); oacc[j] = (f32x4){0.f, 0.f, 0.f, 0.f}; }
;     const float g8 = exp2f(lg * 8.0f);
;     const size_t sbase = (((size_t)l * 128 + b) * 8 + h) * 65536;
;     const float* Sin = p.state_ret + sbase; float* Sout = pout(p) + O_RS + sbase;
;     f32x4 S4[8], N4[8];
; #pragma unroll
;     for (int u = 0; u < 8; ++u) S4[u] = __builtin_nontemporal_load((const f32x4*)(Sin + (size_t)(wid * 32 + u) * 256 + e4));
.LBB0_522:
	s_and_b64 vcc, exec, s[0:1]
	s_cbranch_vccz .LBB0_544
	v_mov_b32_e32 v0, v244
	s_and_b32 s9, s38, 7
	v_ashrrev_i32_e32 v138, 6, v0
	v_and_b32_e32 v139, 63, v0
	v_cvt_f32_ubyte0_e32 v0, s9
	v_sub_f32_e32 v0, 0xc0a00000, v0
	v_cmp_gt_f32_e32 vcc, s75, v0
	s_and_b32 s8, s38, -8
	s_and_b64 s[0:1], vcc, exec
	v_cndmask_b32_e32 v2, 0, v237, vcc
	v_add_f32_e32 v0, v0, v2
	v_exp_f32_e32 v0, v0
	s_cselect_b32 s0, 0xffffffc0, 0
	s_lshl_b32 s90, s9, 9
	v_ldexp_f32 v10, v0, s0
	v_sub_f32_e32 v0, 1.0, v10
	v_add_f32_e32 v2, -1.0, v0
	v_sub_f32_e32 v3, v2, v0
	v_add_f32_e32 v3, 1.0, v3
	v_sub_f32_e64 v2, -v10, v2
	v_add_f32_e32 v4, v2, v3
	v_frexp_mant_f32_e32 v5, v0
	v_cvt_f64_f32_e32 v[2:3], v0
	s_mov_b32 s0, 0x3f2aaaab
	v_frexp_exp_i32_f64_e32 v2, v[2:3]
	v_cmp_gt_f32_e32 vcc, s0, v5
	v_readlane_b32 s0, v253, 19
	v_readlane_b32 s1, v253, 20
	v_subbrev_co_u32_e32 v11, vcc, 0, v2, vcc
	v_sub_u32_e32 v2, 0, v11
	v_ldexp_f32 v0, v0, v2
	v_add_f32_e32 v3, -1.0, v0
	v_add_f32_e32 v6, 1.0, v0
	v_ldexp_f32 v2, v4, v2
	v_add_f32_e32 v4, 1.0, v3
	v_add_f32_e32 v7, -1.0, v6
	v_sub_f32_e32 v4, v0, v4
	v_sub_f32_e32 v0, v0, v7
	v_add_f32_e32 v0, v2, v0
	v_add_f32_e32 v12, v6, v0
	v_rcp_f32_e32 v14, v12
	v_add_f32_e32 v4, v2, v4
	v_add_f32_e32 v5, v3, v4
	v_sub_f32_e32 v2, v12, v6
	v_mul_f32_e32 v15, v5, v14
	v_sub_f32_e32 v13, v0, v2
	v_mul_f32_e32 v0, v12, v15
	v_fma_f32 v9, v15, v12, -v0
	v_fmac_f32_e32 v9, v15, v13
	v_add_f32_e32 v2, v0, v9
	v_sub_f32_e32 v17, v5, v2
	v_sub_f32_e32 v3, v5, v3
	v_sub_f32_e32 v16, v2, v0
	v_sub_f32_e32 v0, v5, v17
	v_sub_f32_e32 v8, v4, v3
	v_sub_f32_e32 v18, v0, v2
	v_add_u32_e32 v0, s8, v138
	v_mov_b64_e32 v[2:3], s[0:1]
	v_mad_i64_i32 v[140:141], s[0:1], v0, s74, v[2:3]
	v_lshl_add_u64 v[2:3], v[140:141], 0, s[90:91]
	v_lshlrev_b32_e32 v0, 3, v139
	v_lshl_add_u64 v[2:3], v[2:3], 0, v[0:1]
	s_movk_i32 s0, 0x2000
	v_add_f32_e32 v0, v8, v18
	v_sub_f32_e32 v8, v16, v9
	v_add_co_u32_e32 v4, vcc, s0, v2
	v_add_f32_e32 v0, v8, v0
	s_nop 0
	v_addc_co_u32_e32 v5, vcc, 0, v3, vcc
	v_add_f32_e32 v16, v17, v0
	global_load_dwordx2 v[6:7], v[4:5], off offset:-4096
	global_load_dwordx2 v[8:9], v[4:5], off
	v_mul_f32_e32 v18, v14, v16
	v_mul_f32_e32 v4, v12, v18
	v_fma_f32 v5, v18, v12, -v4
	v_fmac_f32_e32 v5, v18, v13
	v_sub_f32_e32 v12, v17, v16
	v_add_f32_e32 v0, v0, v12
	v_add_f32_e32 v12, v4, v5
	v_sub_f32_e32 v17, v16, v12
	s_movk_i32 s0, 0x3000
	v_sub_f32_e32 v13, v16, v17
	v_add_co_u32_e32 v2, vcc, s0, v2
	v_sub_f32_e32 v4, v12, v4
	v_sub_f32_e32 v12, v13, v12
	v_addc_co_u32_e32 v3, vcc, 0, v3, vcc
	v_add_f32_e32 v0, v0, v12
	global_load_dwordx2 v[12:13], v[2:3], off
	s_lshl_b32 s20, s9, 10
	s_add_u32 s20, s34, s20
	s_addc_u32 s21, s35, 0
	v_lshlrev_b32_e32 v232, 4, v139
	global_load_dwordx4 v[226:229], v232, s[20:21]
	s_mov_b64 s[20:21], 0x1000
	v_lshl_add_u64 v[232:233], v[2:3], 0, s[20:21]
	global_load_dwordx2 v[230:231], v[232:233], off
	s_ashr_i32 s12, s38, 3
	s_ashr_i32 s13, s12, 31
	s_lshl_b64 s[12:13], s[12:13], 3
	s_add_u32 s12, s12, s26
	s_addc_u32 s13, s13, s27
	s_or_b32 s12, s12, s9
	s_lshl_b64 s[12:13], s[12:13], 18
	s_add_u32 s12, s50, s12
	s_addc_u32 s13, s51, s13
	v_lshlrev_b32_e32 v102, 4, v139
	v_lshl_add_u32 v102, v138, 15, v102
	s_add_u32 s14, s12, 0x1000
	s_addc_u32 s15, s13, 0
	s_add_u32 s16, s12, 0x2000
	s_addc_u32 s17, s13, 0
	s_add_u32 s18, s12, 0x3000
	s_addc_u32 s19, s13, 0
	global_load_dwordx4 v[86:89], v102, s[12:13] nt
	global_load_dwordx4 v[78:81], v102, s[12:13] offset:1024 nt
	global_load_dwordx4 v[74:77], v102, s[12:13] offset:2048 nt
	global_load_dwordx4 v[62:65], v102, s[12:13] offset:3072 nt
	global_load_dwordx4 v[54:57], v102, s[14:15] nt
	global_load_dwordx4 v[38:41], v102, s[14:15] offset:1024 nt
	global_load_dwordx4 v[46:49], v102, s[14:15] offset:2048 nt
	global_load_dwordx4 v[98:101], v102, s[14:15] offset:3072 nt
	global_load_dwordx4 v[90:93], v102, s[16:17] nt
	global_load_dwordx4 v[82:85], v102, s[16:17] offset:1024 nt
	global_load_dwordx4 v[70:73], v102, s[16:17] offset:2048 nt
	global_load_dwordx4 v[66:69], v102, s[16:17] offset:3072 nt
	global_load_dwordx4 v[58:61], v102, s[18:19] nt
	global_load_dwordx4 v[50:53], v102, s[18:19] offset:1024 nt
	global_load_dwordx4 v[42:45], v102, s[18:19] offset:2048 nt
	global_load_dwordx4 v[34:37], v102, s[18:19] offset:3072 nt
	v_sub_f32_e32 v2, v4, v5
	v_cvt_f32_i32_e32 v4, v11
	v_add_f32_e32 v0, v2, v0
	v_add_f32_e32 v2, v15, v18
	v_add_f32_e32 v0, v17, v0
	v_sub_f32_e32 v3, v2, v15
	v_mul_f32_e32 v0, v14, v0
	v_sub_f32_e32 v3, v18, v3
	v_add_f32_e32 v0, v3, v0
	v_mul_f32_e32 v14, 0x3f317218, v4
	s_mov_b32 s0, 0x3f317218
	v_add_f32_e32 v3, v2, v0
	v_fma_f32 v15, v4, s0, -v14
	v_mul_f32_e32 v5, v3, v3
	v_fmac_f32_e32 v15, 0xb102e308, v4
	v_sub_f32_e32 v2, v3, v2
	v_fmamk_f32 v11, v5, 0x3e9b6dac, v234
	v_sub_f32_e32 v0, v0, v2
	v_add_f32_e32 v2, v14, v15
	v_fmaak_f32 v11, v5, v11, 0x3f2aaada
	v_sub_f32_e32 v4, v2, v14
	v_ldexp_f32 v14, v3, 1
	v_mul_f32_e32 v3, v3, v5
	v_mul_f32_e32 v3, v3, v11
	v_add_f32_e32 v5, v14, v3
	v_sub_f32_e32 v11, v5, v14
	v_ldexp_f32 v0, v0, 1
	v_sub_f32_e32 v3, v3, v11
	v_add_f32_e32 v0, v0, v3
	v_add_f32_e32 v3, v5, v0
	v_sub_f32_e32 v5, v3, v5
	v_sub_f32_e32 v0, v0, v5
	v_add_f32_e32 v5, v2, v3
	v_sub_f32_e32 v11, v5, v2
	v_sub_f32_e32 v14, v5, v11
	v_sub_f32_e32 v4, v15, v4
	v_sub_f32_e32 v2, v2, v14
	v_sub_f32_e32 v3, v3, v11
	v_add_f32_e32 v2, v3, v2
	v_add_f32_e32 v3, v4, v0
	v_sub_f32_e32 v11, v3, v4
	v_sub_f32_e32 v14, v3, v11
	v_add_f32_e32 v2, v3, v2
	v_sub_f32_e32 v4, v4, v14
	v_sub_f32_e32 v0, v0, v11
	v_add_f32_e32 v3, v5, v2
	v_add_f32_e32 v0, v0, v4
	v_sub_f32_e32 v4, v3, v5
	v_sub_f32_e32 v2, v2, v4
	v_add_f32_e32 v0, v0, v2
	v_add_f32_e32 v0, v3, v0
	v_cmp_nlt_f32_e32 vcc, 1.0, v10
	s_mov_b32 s0, 0x33800000
	v_lshl_add_u32 v14, v138, 10, 0
	v_cndmask_b32_e32 v0, v238, v0, vcc
	v_cmp_neq_f32_e32 vcc, 1.0, v10
	v_lshlrev_b32_e32 v15, 4, v139
	v_add_u32_e32 v16, v14, v15
	v_cndmask_b32_e32 v0, v239, v0, vcc
	v_cmp_gt_f32_e32 vcc, s0, v10
	s_waitcnt vmcnt(18)
; #define LAS __attribute__((address_space(3)))
; __device__ __forceinline__ float bf_lo(unsigned u) { return __uint_as_float(u << 16); }
; __device__ __forceinline__ float bf_hi(unsigned u) { return __uint_as_float(u & 0xffff0000u); }
; __device__ void sample_ret_unit(const Params& p, int l, int unit, LAS unsigned char* lds, const int tid_in) {
;     ...
;     { const int i = tid >> 6, d = (tid & 63) * 4; const bf16_t* zr = zb + (size_t)(r0 + i) * ZW + h * 256 + d;
;         const u32x2 a = *(const u32x2*)(zr + ZC_Q), kk = *(const u32x2*)(zr + ZC_K), vv = *(const u32x2*)(zr + ZC_V);
;         const float qf[4] = {bf_lo(a.x), bf_hi(a.x), bf_lo(a.y), bf_hi(a.y)}, kf[4] = {bf_lo(kk.x), bf_hi(kk.x), bf_lo(kk.y), bf_hi(kk.y)};
;         const float dk = exp2f(lg * (float)(7 - i));
;         *(LAS f32x4*)(sq + i * 256 + d) = (f32x4){qf[0], qf[1], qf[2], qf[3]};
;         *(LAS f32x4*)(sk + i * 256 + d) = (f32x4){kf[0], kf[1], kf[2], kf[3]};
;         *(LAS f32x4*)(sv + i * 256 + d) = (f32x4){bf_lo(vv.x), bf_hi(vv.x), bf_lo(vv.y), bf_hi(vv.y)};
; #pragma unroll
;         for (int j = 0; j < 4; ++j) { sqT[(d + j) * 8 + i] = qf[j]; skdT[(d + j) * 8 + i] = kf[j] * dk; } }
;     __syncthreads();
;     { const int i = wid; const f32x4 qv = *(const LAS f32x4*)(sq + i * 256 + lane * 4);
;         for (int j = 0; j < 8; ++j) { const f32x4 kv = *(const LAS f32x4*)(sk + j * 256 + lane * 4);
;             float s = wave_sum(qv[0] * kv[0] + qv[1] * kv[1] + qv[2] * kv[2] + qv[3] * kv[3]);
;             if (lane == 0) sc[i * 8 + j] = j <= i ? s * exp2f(lg * (float)(i - j)) : 0.f; } }
	v_lshlrev_b32_e32 v2, 16, v6
	v_and_b32_e32 v3, 0xffff0000, v6
	v_cndmask_b32_e64 v0, v0, -v10, vcc
	v_mul_f32_e32 v145, 0x3fb8aa3b, v0
	v_sub_u32_e32 v0, 7, v138
	v_cvt_f32_i32_e32 v0, v0
	v_lshlrev_b32_e32 v4, 16, v7
	v_and_b32_e32 v5, 0xffff0000, v7
	v_lshlrev_b32_e32 v6, 16, v8
	v_and_b32_e32 v7, 0xffff0000, v8
	v_mul_f32_e32 v8, v145, v0
	v_cmp_gt_f32_e32 vcc, s75, v8
	v_add_u32_e32 v18, 0, v15
	s_movk_i32 s0, 0xfc20
	v_cndmask_b32_e32 v8, 0, v237, vcc
	v_fmac_f32_e32 v8, v145, v0
	v_exp_f32_e32 v0, v8
	v_cndmask_b32_e32 v10, 0, v240, vcc
	v_lshlrev_b32_e32 v8, 16, v9
	v_and_b32_e32 v11, 0xffff0000, v12
	v_ldexp_f32 v0, v0, v10
	v_lshlrev_b32_e32 v10, 16, v12
	v_lshlrev_b32_e32 v12, 16, v13
	v_and_b32_e32 v13, 0xffff0000, v13
	v_and_b32_e32 v9, 0xffff0000, v9
	ds_write_b128 v16, v[2:5]
	ds_write_b128 v16, v[6:9] offset:8192
	ds_write_b128 v16, v[10:13] offset:16384
	v_lshl_add_u32 v10, v139, 5, v138
	v_lshl_add_u32 v10, v10, 2, 0
	v_add_u32_e32 v11, 0x6000, v10
	v_mul_f32_e32 v6, v0, v6
	ds_write2_b32 v11, v2, v3 offset1:8
	v_mul_f32_e32 v2, v0, v7
	v_add_u32_e32 v3, 0x8000, v10
	ds_write2_b32 v3, v6, v2 offset1:8
	v_mul_f32_e32 v2, v0, v8
	v_mul_f32_e32 v0, v0, v9
	ds_write2_b32 v11, v4, v5 offset0:16 offset1:24
	ds_write2_b32 v3, v2, v0 offset0:16 offset1:24
	s_waitcnt lgkmcnt(0)
	s_barrier
	ds_read_b128 v[2:5], v16
	ds_read_b128 v[6:9], v18 offset:8192
	v_mul_lo_u32 v0, v138, s0
	v_cmp_eq_u32_e32 vcc, 0, v139
	v_add_u32_e32 v0, v14, v0
	s_waitcnt lgkmcnt(0)
	v_mul_f32_e32 v7, v3, v7
	v_fmac_f32_e32 v7, v2, v6
	v_fmac_f32_e32 v7, v4, v8
	v_fmac_f32_e32 v7, v5, v9
	s_nop 1
	v_add_f32_dpp v6, v7, v7 quad_perm:[1,0,3,2] row_mask:0xf bank_mask:0xf bound_ctrl:1
	s_nop 1
	v_add_f32_dpp v6, v6, v6 quad_perm:[2,3,0,1] row_mask:0xf bank_mask:0xf bound_ctrl:1
	s_nop 1
	v_add_f32_dpp v6, v6, v6 row_half_mirror row_mask:0xf bank_mask:0xf bound_ctrl:1
	s_nop 1
	v_add_f32_dpp v6, v6, v6 row_mirror row_mask:0xf bank_mask:0xf bound_ctrl:1
	s_nop 0
	v_readlane_b32 s6, v6, 0
	v_readlane_b32 s10, v6, 16
	v_readlane_b32 s7, v6, 32
	v_readlane_b32 s11, v6, 48
	s_and_saveexec_b64 s[0:1], vcc
	s_cbranch_execz .LBB0_525
	v_mov_b32_e32 v6, s10
	v_mov_b32_e32 v7, s11
	v_pk_add_f32 v[6:7], s[6:7], v[6:7]
	s_nop 0
	v_add_f32_e32 v6, v6, v7
	v_cvt_f32_i32_e32 v7, v138
	v_mul_f32_e32 v8, v145, v7
	v_cmp_gt_f32_e64 s[6:7], s75, v8
	s_nop 1
	v_cndmask_b32_e64 v9, 0, v237, s[6:7]
	v_fmac_f32_e32 v9, v145, v7
	v_exp_f32_e32 v7, v9
	v_cndmask_b32_e64 v8, 0, v240, s[6:7]
	v_cmp_lt_i32_e64 s[6:7], -1, v138
	v_ldexp_f32 v7, v7, v8
	v_mul_f32_e32 v6, v7, v6
	v_cndmask_b32_e64 v6, 0, v6, s[6:7]
	ds_write_b32 v0, v6 offset:40960

; #define LAS __attribute__((address_space(3)))
; __device__ __forceinline__ unsigned pk_bf16(float lo, float hi) { unsigned r; asm volatile("v_cvt_pk_bf16_f32 %0, %1, %2" : "=v"(r) : "v"(lo), "v"(hi)); return r; }
; __device__ __forceinline__ float bf_lo(unsigned u) { return __uint_as_float(u << 16); }
; __device__ __forceinline__ float bf_hi(unsigned u) { return __uint_as_float(u & 0xffff0000u); }
; __device__ void sample_ret_unit(const Params& p, int l, int unit, LAS unsigned char* lds, const int tid_in) {
;     ...
;         o *= exp2f(lg * (float)(i + 1));
;         for (int j = 0; j <= i; ++j) o += *(const LAS f32x4*)(sv + j * 256 + e4) * sc[i * 8 + j];
;         const float mu = wave_sum(o[0] + o[1] + o[2] + o[3]) * (1.0f / 256.0f);
;         o -= mu;
;         const float var = wave_sum(o[0] * o[0] + o[1] * o[1] + o[2] * o[2] + o[3] * o[3]) * (1.0f / 256.0f);
;         const float rs = rsqrtf(var + EPS);
;         const f32x4 gn = *(const f32x4*)(p.ret_gn + (size_t)l * D + h * 256 + e4);
;         const u32x2 rg = *(const u32x2*)(zb + (size_t)(r0 + i) * ZW + ZC_RG + h * 256 + e4);
;         u32x2 w; w.x = pk_bf16(o[0] * rs * gn[0] * bf_lo(rg.x), o[1] * rs * gn[1] * bf_hi(rg.x)); w.y = pk_bf16(o[2] * rs * gn[2] * bf_lo(rg.y), o[3] * rs * gn[3] * bf_hi(rg.y));
;         *(u32x2*)((bf16_t*)(pws(p) + OFF_AIN) + ((size_t)MPAD + r0 + i) * D + h * 256 + e4) = w; }
;     __syncthreads();
.LBB0_543:
	s_or_b64 exec, exec, s[0:1]
	v_add_f32_e32 v6, v2, v3
	v_add_f32_e32 v6, v4, v6
	v_add_f32_e32 v6, v5, v6
	s_lshl_b32 s0, s9, 8
	v_ashrrev_i32_e32 v139, 31, v138
	v_add_f32_dpp v6, v6, v6 quad_perm:[1,0,3,2] row_mask:0xf bank_mask:0xf bound_ctrl:1
	s_nop 1
	v_add_f32_dpp v6, v6, v6 quad_perm:[2,3,0,1] row_mask:0xf bank_mask:0xf bound_ctrl:1
	s_nop 1
	v_add_f32_dpp v6, v6, v6 row_half_mirror row_mask:0xf bank_mask:0xf bound_ctrl:1
	s_nop 1
	v_add_f32_dpp v6, v6, v6 row_mirror row_mask:0xf bank_mask:0xf bound_ctrl:1
	s_nop 0
	v_readlane_b32 s1, v6, 16
	v_readlane_b32 s9, v6, 48
	v_readlane_b32 s6, v6, 0
	v_readlane_b32 s7, v6, 32
	v_mov_b32_e32 v6, s1
	v_mov_b32_e32 v7, s9
	v_pk_add_f32 v[6:7], s[6:7], v[6:7]
	s_nop 0
	v_add_f32_e32 v6, v6, v7
	v_fmamk_f32 v3, v6, 0xbb800000, v3
	v_fmamk_f32 v2, v6, 0xbb800000, v2
	v_fmamk_f32 v5, v6, 0xbb800000, v5
	v_fmac_f32_e32 v4, 0xbb800000, v6
	v_pk_mul_f32 v[8:9], v[2:3], v[2:3]
	v_pk_mul_f32 v[6:7], v[4:5], v[4:5]
	v_add_f32_e32 v8, v8, v9
	v_add_f32_e32 v6, v6, v8
	v_add_f32_e32 v6, v7, v6
	s_nop 1
	v_add_f32_dpp v6, v6, v6 quad_perm:[1,0,3,2] row_mask:0xf bank_mask:0xf bound_ctrl:1
	s_nop 1
	v_add_f32_dpp v6, v6, v6 quad_perm:[2,3,0,1] row_mask:0xf bank_mask:0xf bound_ctrl:1
	s_nop 1
	v_add_f32_dpp v6, v6, v6 row_half_mirror row_mask:0xf bank_mask:0xf bound_ctrl:1
	s_nop 1
	v_add_f32_dpp v6, v6, v6 row_mirror row_mask:0xf bank_mask:0xf bound_ctrl:1
	s_nop 0
	v_readlane_b32 s1, v6, 16
	v_readlane_b32 s9, v6, 48
	v_readlane_b32 s6, v6, 0
	v_readlane_b32 s7, v6, 32
	v_mov_b32_e32 v6, s1
	v_mov_b32_e32 v7, s9
	v_pk_add_f32 v[6:7], s[6:7], v[6:7]
	s_lshl_b32 s1, s0, 2
	v_add_f32_e32 v6, v6, v7
	v_fmamk_f32 v6, v6, 0x3b800000, v190
	v_cmp_gt_f32_e32 vcc, s78, v6
	v_mul_f32_e32 v7, 0x4b800000, v6
	s_add_u32 s6, s34, s1
	v_cndmask_b32_e32 v6, v6, v7, vcc
	v_rsq_f32_e32 v6, v6
	s_addc_u32 s7, s35, 0
	s_lshl_b32 s90, s0, 1
	v_mul_f32_e32 v7, 0x45800000, v6
	v_cndmask_b32_e32 v12, v6, v7, vcc
	v_lshlrev_b32_e32 v0, 1, v180
	s_movk_i32 s0, 0x4000
	v_mul_f32_e32 v2, v2, v12
	s_nop 0
	v_mul_f32_e32 v3, v3, v12
	s_ashr_i32 s1, s8, 31
	s_add_u32 s0, s8, 0x2500
	s_addc_u32 s1, s1, 0
	s_mov_b64 s[6:7], -1
	v_mul_f32_e32 v2, v226, v2
	v_mul_f32_e32 v3, v227, v3
	v_lshlrev_b32_e32 v6, 16, v230
	v_mul_f32_e32 v2, v2, v6
	v_and_b32_e32 v6, 0xffff0000, v230
	v_mul_f32_e32 v3, v3, v6
	v_cvt_pk_bf16_f32 v2, v2, v3
	v_mul_f32_e32 v3, v4, v12
	v_mul_f32_e32 v3, v228, v3
	v_lshlrev_b32_e32 v4, 16, v231
	v_mul_f32_e32 v3, v3, v4
	v_mul_f32_e32 v4, v5, v12
	v_mul_f32_e32 v4, v229, v4
	v_and_b32_e32 v5, 0xffff0000, v231
	v_mul_f32_e32 v4, v4, v5
	v_cvt_pk_bf16_f32 v3, v3, v4
	v_lshl_add_u64 v[4:5], s[0:1], 0, v[138:139]
	v_lshlrev_b64 v[4:5], 12, v[4:5]
	v_lshl_add_u64 v[4:5], s[96:97], 0, v[4:5]
	v_lshl_add_u64 v[4:5], v[4:5], 0, s[90:91]
	v_lshl_add_u64 v[4:5], v[4:5], 0, v[0:1]
	global_store_dwordx2 v[4:5], v[2:3], off
	s_barrier
